# grid barrier: each XCD's second-to-last arriver starts an early L2 write-back
# baseline (speedup 1.0000x reference)
.LBB0_632:
	v_readlane_b32 s2, v248, 16
	v_readlane_b32 s3, v248, 17
	v_cvt_f32_u32_e32 v1, v4
	v_sub_u32_e32 v6, 0, v4
	v_rcp_iflag_f32_e32 v1, v1
	s_nop 1
	global_atomic_add v5, v3, v202, s[2:3] sc0
	v_mul_f32_e32 v1, 0x4f7ffffe, v1
	v_cvt_u32_f32_e32 v1, v1
	v_mul_lo_u32 v6, v6, v1
	v_mul_hi_u32 v6, v1, v6
	v_add_u32_e32 v1, v1, v6
	s_waitcnt vmcnt(0)
	v_mul_hi_u32 v1, v5, v1
	v_mul_lo_u32 v6, v1, v4
	v_sub_u32_e32 v6, v5, v6
	v_add_u32_e32 v7, 1, v1
	v_cmp_ge_u32_e32 vcc, v6, v4
	v_add_u32_e32 v5, 1, v5
	s_nop 0
	v_cndmask_b32_e32 v1, v1, v7, vcc
	v_sub_u32_e32 v7, v6, v4
	v_cndmask_b32_e32 v6, v6, v7, vcc
	v_add_u32_e32 v7, 1, v1
	v_cmp_ge_u32_e32 vcc, v6, v4
	s_nop 1
	v_cndmask_b32_e32 v1, v1, v7, vcc
	v_mul_lo_u32 v6, v4, v1
	v_add_u32_e32 v4, v6, v4
	v_cmp_ne_u32_e32 vcc, v5, v4
	s_and_saveexec_b64 s[6:7], vcc
	s_xor_b64 s[6:7], exec, s[6:7]
	s_cbranch_execz .LBB0_646
	v_add_u32_e32 v6, 1, v5
	v_cmp_eq_u32_e32 vcc, v6, v4
	s_cbranch_vccz .Lwb2_skip_0
	buffer_wbl2 sc1
.Lwb2_skip_0:
	v_readlane_b32 s2, v248, 18
	v_readlane_b32 s3, v248, 19
	s_waitcnt lgkmcnt(0)
	s_nop 3
	global_load_dword v2, v3, s[2:3] sc1
	s_waitcnt vmcnt(0)
	v_cmp_eq_u32_e32 vcc, v2, v1
	s_and_saveexec_b64 s[8:9], vcc
	s_cbranch_execz .LBB0_645
	s_mov_b32 s21, 1
	s_mov_b64 s[10:11], 0
	s_branch .LBB0_636

.LBB0_1177:
	v_readlane_b32 s2, v248, 16
	v_readlane_b32 s3, v248, 17
	v_cvt_f32_u32_e32 v1, v4
	v_sub_u32_e32 v6, 0, v4
	v_rcp_iflag_f32_e32 v1, v1
	s_nop 1
	global_atomic_add v5, v3, v202, s[2:3] sc0
	v_mul_f32_e32 v1, 0x4f7ffffe, v1
	v_cvt_u32_f32_e32 v1, v1
	v_mul_lo_u32 v6, v6, v1
	v_mul_hi_u32 v6, v1, v6
	v_add_u32_e32 v1, v1, v6
	s_waitcnt vmcnt(0)
	v_mul_hi_u32 v1, v5, v1
	v_mul_lo_u32 v6, v1, v4
	v_sub_u32_e32 v6, v5, v6
	v_add_u32_e32 v7, 1, v1
	v_cmp_ge_u32_e32 vcc, v6, v4
	v_add_u32_e32 v5, 1, v5
	s_nop 0
	v_cndmask_b32_e32 v1, v1, v7, vcc
	v_sub_u32_e32 v7, v6, v4
	v_cndmask_b32_e32 v6, v6, v7, vcc
	v_add_u32_e32 v7, 1, v1
	v_cmp_ge_u32_e32 vcc, v6, v4
	s_nop 1
	v_cndmask_b32_e32 v1, v1, v7, vcc
	v_mul_lo_u32 v6, v4, v1
	v_add_u32_e32 v4, v6, v4
	v_cmp_ne_u32_e32 vcc, v5, v4
	s_and_saveexec_b64 s[8:9], vcc
	s_xor_b64 s[8:9], exec, s[8:9]
	s_cbranch_execz .LBB0_1191
	v_add_u32_e32 v6, 1, v5
	v_cmp_eq_u32_e32 vcc, v6, v4
	s_cbranch_vccz .Lwb2_skip_4
	buffer_wbl2 sc1
.Lwb2_skip_4:
	v_readlane_b32 s2, v248, 18
	v_readlane_b32 s3, v248, 19
	s_waitcnt lgkmcnt(0)
	s_nop 3
	global_load_dword v2, v3, s[2:3] sc1
	s_waitcnt vmcnt(0)
	v_cmp_eq_u32_e32 vcc, v2, v1
	s_and_saveexec_b64 s[10:11], vcc
	s_cbranch_execz .LBB0_1190
	s_mov_b32 s25, 1
	s_mov_b64 s[12:13], 0
	s_branch .LBB0_1181

.Lwb2_skip_7:
	v_readlane_b32 s2, v248, 18
	v_readlane_b32 s3, v248, 19
	s_waitcnt lgkmcnt(0)
	s_nop 3
	global_load_dword v2, v3, s[2:3] sc1
	s_waitcnt vmcnt(0)
	v_cmp_eq_u32_e32 vcc, v2, v1
	s_and_saveexec_b64 s[8:9], vcc
	s_cbranch_execz .LBB0_1404
	s_mov_b32 s20, 1
	s_mov_b64 s[10:11], 0
	s_branch .LBB0_1395
